# weight conversion: per-job first-tile owner rotated by the tiles of the previous jobs so per-job remainders spread over all workgroups (max 10 tile iterations per workgroup instead of 15)
# speedup vs baseline: 1.0060x; 1.0060x over previous
;     DI unsigned char* ws() const { return (unsigned char*)gp(35); }
; DI int fresh_tid(const Params& P) { int t = P.tid; asm volatile("" : "+v"(t)); return t; }
; DI void cvt_job(const float* __restrict__ src, int K, int N, int Npad, bf16_t* __restrict__ dst, int mode, float* tile, const int tid) {
;     ...
;     for (int t = blockIdx.x; t < ntile; t += gridDim.x) {
; DI void convert_jobs(const Params& P, int l, int jlo, int jhi, unsigned char* shm) {
;     const int tid_ = fresh_tid(P);
;     float* tile = (float*)shm; unsigned char* ws = P.ws();
; #pragma nounroll
;     for (int j = jlo; j < jhi; ++j) {
.LBB0_451:
	s_sub_i32 s93, s93, s17
.Lcvt_rot:
	s_cmp_lt_i32 s93, 0
	s_cbranch_scc0 .Lcvt_rot_done
	s_add_i32 s93, s93, s94
	s_branch .Lcvt_rot
.Lcvt_rot_done:
	s_lshl_b32 s89, s93, 6
	s_add_i32 s20, s20, 1
	s_cmp_lt_u32 s20, s5
	s_cbranch_scc0 .LBB0_519
